# EpiSwiglu epilogues (4 up-GEMMs): 64-bit mad address chain replaced by 32-bit offset + SGPR-base stores
# speedup vs baseline: 1.0070x; 1.0000x over previous
; __device__ __forceinline__ unsigned cvt_pk_bf16(float lo, float hi) { unsigned r; asm("v_cvt_pk_bf16_f32 %0, %1, %2" : "=v"(r) : "v"(lo), "v"(hi)); return r; }
;     __device__ __forceinline__ void operator()(const Acc& acc, const Unit& u, int wr, int wc, int fr, int fq) const {
;         const int row0 = u.pm * 256 + wr * 64 + fr, h0 = u.pn * 128 + wc * 32 + 8 * fq;
; #pragma unroll
;         for (int ai = 0; ai < 2; ++ai)
; #pragma unroll
;             for (int m = 0; m < 4; ++m) { bf16_t* rp = ACT + (size_t)(row0 + ai * 128 + m * 16) * FF + h0; float v[8];
; #pragma unroll
;                 for (int n = 0; n < 2; ++n) { const f32x4 a = acc[ai][0][m][n], b = acc[ai][1][m][n];
;                     const f32x4 t = a * (-LOG2E); f32x4 e; e.x = __builtin_amdgcn_exp2f(t.x); e.y = __builtin_amdgcn_exp2f(t.y); e.z = __builtin_amdgcn_exp2f(t.z); e.w = __builtin_amdgcn_exp2f(t.w);
;                     const f32x4 d = e + 1.0f; f32x4 r; r.x = __builtin_amdgcn_rcpf(d.x); r.y = __builtin_amdgcn_rcpf(d.y); r.z = __builtin_amdgcn_rcpf(d.z); r.w = __builtin_amdgcn_rcpf(d.w);
;                     const f32x4 o = (a * b) * r; v[4 * n + 0] = o.x; v[4 * n + 1] = o.y; v[4 * n + 2] = o.z; v[4 * n + 3] = o.w; }
;                 u32x4 w; w.x = cvt_pk_bf16(v[0], v[1]); w.y = cvt_pk_bf16(v[2], v[3]); w.z = cvt_pk_bf16(v[4], v[5]); w.w = cvt_pk_bf16(v[6], v[7]); __builtin_nontemporal_store(w, (u32x4*)rp); }
.LBB0_259:
	v_pk_mul_f32 v[152:153], v[126:127], s[10:11] op_sel_hi:[1,0]
	v_pk_mul_f32 v[122:123], v[126:127], v[122:123]
	v_pk_mul_f32 v[126:127], v[116:117], s[10:11] op_sel_hi:[1,0]
	v_pk_mul_f32 v[154:155], v[124:125], s[10:11] op_sel_hi:[1,0]
	v_pk_mul_f32 v[120:121], v[124:125], v[120:121]
	v_pk_mul_f32 v[124:125], v[118:119], s[10:11] op_sel_hi:[1,0]
	v_exp_f32_e32 v126, v126
	v_exp_f32_e32 v127, v127
	v_exp_f32_e32 v154, v154
	v_exp_f32_e32 v152, v152
	v_exp_f32_e32 v153, v153
	v_exp_f32_e32 v155, v155
	v_exp_f32_e32 v124, v124
	v_exp_f32_e32 v125, v125
	v_pk_add_f32 v[126:127], v[126:127], 1.0 op_sel_hi:[1,0]
	v_pk_add_f32 v[152:153], v[152:153], 1.0 op_sel_hi:[1,0]
	v_pk_add_f32 v[154:155], v[154:155], 1.0 op_sel_hi:[1,0]
	v_pk_add_f32 v[124:125], v[124:125], 1.0 op_sel_hi:[1,0]
	v_rcp_f32_e32 v126, v126
	v_rcp_f32_e32 v127, v127
	v_rcp_f32_e32 v154, v154
	v_rcp_f32_e32 v155, v155
	v_rcp_f32_e32 v152, v152
	v_rcp_f32_e32 v153, v153
	v_rcp_f32_e32 v124, v124
	v_rcp_f32_e32 v125, v125
	v_lshl_or_b32 v150, s57, 7, v144
	v_lshl_add_u32 v148, s42, 8, v142
	v_pk_mul_f32 v[112:113], v[116:117], v[112:113]
	v_mul_u32_u24_e32 v140, s56, v148
	v_pk_mul_f32 v[114:115], v[118:119], v[114:115]
	v_pk_mul_f32 v[116:117], v[126:127], v[112:113]
	v_pk_mul_f32 v[122:123], v[152:153], v[122:123]
	v_pk_mul_f32 v[120:121], v[154:155], v[120:121]
	v_pk_mul_f32 v[118:119], v[124:125], v[114:115]
	v_lshl_add_u32 v140, v150, 1, v140
	v_cvt_pk_bf16_f32 v114, v120, v121
	v_cvt_pk_bf16_f32 v115, v122, v123
	v_cvt_pk_bf16_f32 v116, v116, v117
	v_cvt_pk_bf16_f32 v117, v118, v119
	global_store_dwordx4 v140, v[114:117], s[14:15] nt
	v_pk_mul_f32 v[106:107], v[110:111], v[106:107]
	v_pk_mul_f32 v[104:105], v[108:109], v[104:105]
	v_pk_mul_f32 v[114:115], v[110:111], s[10:11] op_sel_hi:[1,0]
	v_pk_mul_f32 v[116:117], v[108:109], s[10:11] op_sel_hi:[1,0]
	v_pk_mul_f32 v[108:109], v[102:103], s[10:11] op_sel_hi:[1,0]
	v_pk_mul_f32 v[110:111], v[100:101], s[10:11] op_sel_hi:[1,0]
	v_exp_f32_e32 v108, v108
	v_exp_f32_e32 v110, v110
	v_exp_f32_e32 v109, v109
	v_exp_f32_e32 v111, v111
	v_exp_f32_e32 v116, v116
	v_exp_f32_e32 v114, v114
	v_exp_f32_e32 v115, v115
	v_exp_f32_e32 v117, v117
	v_pk_add_f32 v[108:109], v[108:109], 1.0 op_sel_hi:[1,0]
	v_pk_add_f32 v[110:111], v[110:111], 1.0 op_sel_hi:[1,0]
	v_pk_add_f32 v[114:115], v[114:115], 1.0 op_sel_hi:[1,0]
	v_pk_add_f32 v[116:117], v[116:117], 1.0 op_sel_hi:[1,0]
	v_rcp_f32_e32 v110, v110
	v_rcp_f32_e32 v108, v108
	v_rcp_f32_e32 v109, v109
	v_rcp_f32_e32 v111, v111
	v_rcp_f32_e32 v116, v116
	v_rcp_f32_e32 v117, v117
	v_rcp_f32_e32 v114, v114
	v_rcp_f32_e32 v115, v115
	v_pk_mul_f32 v[98:99], v[102:103], v[98:99]
	v_pk_mul_f32 v[96:97], v[100:101], v[96:97]
	v_pk_mul_f32 v[100:101], v[108:109], v[98:99]
	v_pk_mul_f32 v[98:99], v[110:111], v[96:97]
	v_pk_mul_f32 v[106:107], v[114:115], v[106:107]
	v_pk_mul_f32 v[104:105], v[116:117], v[104:105]
	v_add_u32_e32 v102, 0x16000, v140
	v_cvt_pk_bf16_f32 v96, v104, v105
	v_cvt_pk_bf16_f32 v97, v106, v107
	v_cvt_pk_bf16_f32 v98, v98, v99
	v_cvt_pk_bf16_f32 v99, v100, v101
	global_store_dwordx4 v102, v[96:99], s[14:15] nt
	v_pk_mul_f32 v[90:91], v[94:95], v[90:91]
	v_pk_mul_f32 v[88:89], v[92:93], v[88:89]
	v_pk_mul_f32 v[96:97], v[94:95], s[10:11] op_sel_hi:[1,0]
	v_pk_mul_f32 v[98:99], v[92:93], s[10:11] op_sel_hi:[1,0]
	v_pk_mul_f32 v[92:93], v[86:87], s[10:11] op_sel_hi:[1,0]
	v_pk_mul_f32 v[94:95], v[84:85], s[10:11] op_sel_hi:[1,0]
	v_exp_f32_e32 v92, v92
	v_exp_f32_e32 v94, v94
	v_exp_f32_e32 v93, v93
	v_exp_f32_e32 v95, v95
	v_exp_f32_e32 v98, v98
	v_exp_f32_e32 v96, v96
	v_exp_f32_e32 v97, v97
	v_exp_f32_e32 v99, v99
	v_pk_add_f32 v[92:93], v[92:93], 1.0 op_sel_hi:[1,0]
	v_pk_add_f32 v[94:95], v[94:95], 1.0 op_sel_hi:[1,0]
	v_pk_add_f32 v[96:97], v[96:97], 1.0 op_sel_hi:[1,0]
	v_pk_add_f32 v[98:99], v[98:99], 1.0 op_sel_hi:[1,0]
	v_rcp_f32_e32 v94, v94
	v_rcp_f32_e32 v92, v92
	v_rcp_f32_e32 v93, v93
	v_rcp_f32_e32 v95, v95
	v_rcp_f32_e32 v98, v98
	v_rcp_f32_e32 v99, v99
	v_rcp_f32_e32 v96, v96
	v_rcp_f32_e32 v97, v97
	v_pk_mul_f32 v[82:83], v[86:87], v[82:83]
	v_pk_mul_f32 v[80:81], v[84:85], v[80:81]
	v_pk_mul_f32 v[84:85], v[92:93], v[82:83]
	v_pk_mul_f32 v[82:83], v[94:95], v[80:81]
	v_pk_mul_f32 v[90:91], v[96:97], v[90:91]
	v_pk_mul_f32 v[88:89], v[98:99], v[88:89]
	v_add_u32_e32 v86, 0x2c000, v140
	v_cvt_pk_bf16_f32 v80, v88, v89
	v_cvt_pk_bf16_f32 v81, v90, v91
	v_cvt_pk_bf16_f32 v82, v82, v83
	v_cvt_pk_bf16_f32 v83, v84, v85
	global_store_dwordx4 v86, v[80:83], s[14:15] nt
	v_pk_mul_f32 v[74:75], v[78:79], v[74:75]
	v_pk_mul_f32 v[72:73], v[76:77], v[72:73]
	v_pk_mul_f32 v[80:81], v[78:79], s[10:11] op_sel_hi:[1,0]
	v_pk_mul_f32 v[82:83], v[76:77], s[10:11] op_sel_hi:[1,0]
	v_pk_mul_f32 v[76:77], v[70:71], s[10:11] op_sel_hi:[1,0]
	v_pk_mul_f32 v[78:79], v[68:69], s[10:11] op_sel_hi:[1,0]
	v_exp_f32_e32 v76, v76
	v_exp_f32_e32 v78, v78
	v_exp_f32_e32 v77, v77
	v_exp_f32_e32 v79, v79
	v_exp_f32_e32 v82, v82
	v_exp_f32_e32 v80, v80
	v_exp_f32_e32 v81, v81
	v_exp_f32_e32 v83, v83
	v_pk_add_f32 v[76:77], v[76:77], 1.0 op_sel_hi:[1,0]
	v_pk_add_f32 v[78:79], v[78:79], 1.0 op_sel_hi:[1,0]
	v_pk_add_f32 v[80:81], v[80:81], 1.0 op_sel_hi:[1,0]
	v_pk_add_f32 v[82:83], v[82:83], 1.0 op_sel_hi:[1,0]
	v_rcp_f32_e32 v78, v78
	v_rcp_f32_e32 v76, v76
	v_rcp_f32_e32 v77, v77
	v_rcp_f32_e32 v79, v79
	v_rcp_f32_e32 v82, v82
	v_rcp_f32_e32 v83, v83
	v_rcp_f32_e32 v80, v80
	v_rcp_f32_e32 v81, v81
	v_pk_mul_f32 v[66:67], v[70:71], v[66:67]
	v_pk_mul_f32 v[64:65], v[68:69], v[64:65]
	v_pk_mul_f32 v[68:69], v[76:77], v[66:67]
	v_pk_mul_f32 v[66:67], v[78:79], v[64:65]
; __device__ __forceinline__ unsigned cvt_pk_bf16(float lo, float hi) { unsigned r; asm("v_cvt_pk_bf16_f32 %0, %1, %2" : "=v"(r) : "v"(lo), "v"(hi)); return r; }
;     __device__ __forceinline__ void operator()(const Acc& acc, const Unit& u, int wr, int wc, int fr, int fq) const {
;         const int row0 = u.pm * 256 + wr * 64 + fr, h0 = u.pn * 128 + wc * 32 + 8 * fq;
; #pragma unroll
;         for (int ai = 0; ai < 2; ++ai)
; #pragma unroll
;             for (int m = 0; m < 4; ++m) { bf16_t* rp = ACT + (size_t)(row0 + ai * 128 + m * 16) * FF + h0; float v[8];
; #pragma unroll
;                 for (int n = 0; n < 2; ++n) { const f32x4 a = acc[ai][0][m][n], b = acc[ai][1][m][n];
;                     const f32x4 t = a * (-LOG2E); f32x4 e; e.x = __builtin_amdgcn_exp2f(t.x); e.y = __builtin_amdgcn_exp2f(t.y); e.z = __builtin_amdgcn_exp2f(t.z); e.w = __builtin_amdgcn_exp2f(t.w);
;                     const f32x4 d = e + 1.0f; f32x4 r; r.x = __builtin_amdgcn_rcpf(d.x); r.y = __builtin_amdgcn_rcpf(d.y); r.z = __builtin_amdgcn_rcpf(d.z); r.w = __builtin_amdgcn_rcpf(d.w);
;                     const f32x4 o = (a * b) * r; v[4 * n + 0] = o.x; v[4 * n + 1] = o.y; v[4 * n + 2] = o.z; v[4 * n + 3] = o.w; }
;                 u32x4 w; w.x = cvt_pk_bf16(v[0], v[1]); w.y = cvt_pk_bf16(v[2], v[3]); w.z = cvt_pk_bf16(v[4], v[5]); w.w = cvt_pk_bf16(v[6], v[7]); __builtin_nontemporal_store(w, (u32x4*)rp); }
	v_pk_mul_f32 v[74:75], v[80:81], v[74:75]
	v_pk_mul_f32 v[72:73], v[82:83], v[72:73]
	v_add_u32_e32 v70, 0x42000, v140
	v_cvt_pk_bf16_f32 v64, v72, v73
	v_cvt_pk_bf16_f32 v65, v74, v75
	v_cvt_pk_bf16_f32 v66, v66, v67
	v_cvt_pk_bf16_f32 v67, v68, v69
	global_store_dwordx4 v70, v[64:67], s[14:15] nt
	v_pk_mul_f32 v[58:59], v[62:63], v[58:59]
	v_pk_mul_f32 v[56:57], v[60:61], v[56:57]
	v_pk_mul_f32 v[64:65], v[62:63], s[10:11] op_sel_hi:[1,0]
	v_pk_mul_f32 v[66:67], v[60:61], s[10:11] op_sel_hi:[1,0]
	v_pk_mul_f32 v[60:61], v[54:55], s[10:11] op_sel_hi:[1,0]
	v_pk_mul_f32 v[62:63], v[52:53], s[10:11] op_sel_hi:[1,0]
	v_exp_f32_e32 v60, v60
	v_exp_f32_e32 v62, v62
	v_exp_f32_e32 v61, v61
	v_exp_f32_e32 v63, v63
	v_exp_f32_e32 v66, v66
	v_exp_f32_e32 v64, v64
	v_exp_f32_e32 v65, v65
	v_exp_f32_e32 v67, v67
	v_pk_add_f32 v[60:61], v[60:61], 1.0 op_sel_hi:[1,0]
	v_pk_add_f32 v[62:63], v[62:63], 1.0 op_sel_hi:[1,0]
	v_pk_add_f32 v[64:65], v[64:65], 1.0 op_sel_hi:[1,0]
	v_pk_add_f32 v[66:67], v[66:67], 1.0 op_sel_hi:[1,0]
	v_rcp_f32_e32 v62, v62
	v_rcp_f32_e32 v60, v60
	v_rcp_f32_e32 v61, v61
	v_rcp_f32_e32 v63, v63
	v_rcp_f32_e32 v66, v66
	v_rcp_f32_e32 v67, v67
	v_rcp_f32_e32 v64, v64
	v_rcp_f32_e32 v65, v65
	v_pk_mul_f32 v[50:51], v[54:55], v[50:51]
	v_pk_mul_f32 v[48:49], v[52:53], v[48:49]
	v_pk_mul_f32 v[52:53], v[60:61], v[50:51]
	v_pk_mul_f32 v[50:51], v[62:63], v[48:49]
	v_pk_mul_f32 v[58:59], v[64:65], v[58:59]
	v_pk_mul_f32 v[56:57], v[66:67], v[56:57]
	v_add_u32_e32 v54, 0xb0000, v140
	v_cvt_pk_bf16_f32 v48, v56, v57
	v_cvt_pk_bf16_f32 v49, v58, v59
	v_cvt_pk_bf16_f32 v50, v50, v51
	v_cvt_pk_bf16_f32 v51, v52, v53
	global_store_dwordx4 v54, v[48:51], s[14:15] nt
	v_pk_mul_f32 v[42:43], v[46:47], v[42:43]
	v_pk_mul_f32 v[40:41], v[44:45], v[40:41]
	v_pk_mul_f32 v[48:49], v[46:47], s[10:11] op_sel_hi:[1,0]
	v_pk_mul_f32 v[50:51], v[44:45], s[10:11] op_sel_hi:[1,0]
	v_pk_mul_f32 v[44:45], v[38:39], s[10:11] op_sel_hi:[1,0]
	v_pk_mul_f32 v[46:47], v[36:37], s[10:11] op_sel_hi:[1,0]
	v_exp_f32_e32 v44, v44
	v_exp_f32_e32 v46, v46
	v_exp_f32_e32 v45, v45
	v_exp_f32_e32 v47, v47
	v_exp_f32_e32 v50, v50
	v_exp_f32_e32 v48, v48
	v_exp_f32_e32 v49, v49
	v_exp_f32_e32 v51, v51
	v_pk_add_f32 v[44:45], v[44:45], 1.0 op_sel_hi:[1,0]
	v_pk_add_f32 v[46:47], v[46:47], 1.0 op_sel_hi:[1,0]
	v_pk_add_f32 v[48:49], v[48:49], 1.0 op_sel_hi:[1,0]
	v_pk_add_f32 v[50:51], v[50:51], 1.0 op_sel_hi:[1,0]
	v_rcp_f32_e32 v46, v46
	v_rcp_f32_e32 v44, v44
	v_rcp_f32_e32 v45, v45
	v_rcp_f32_e32 v47, v47
	v_rcp_f32_e32 v50, v50
	v_rcp_f32_e32 v51, v51
	v_rcp_f32_e32 v48, v48
	v_rcp_f32_e32 v49, v49
	v_pk_mul_f32 v[34:35], v[38:39], v[34:35]
	v_pk_mul_f32 v[32:33], v[36:37], v[32:33]
	v_pk_mul_f32 v[36:37], v[44:45], v[34:35]
	v_pk_mul_f32 v[34:35], v[46:47], v[32:33]
	v_pk_mul_f32 v[42:43], v[48:49], v[42:43]
	v_pk_mul_f32 v[40:41], v[50:51], v[40:41]
	v_add_u32_e32 v38, 0xc6000, v140
	v_cvt_pk_bf16_f32 v32, v40, v41
	v_cvt_pk_bf16_f32 v33, v42, v43
	v_cvt_pk_bf16_f32 v34, v34, v35
	v_cvt_pk_bf16_f32 v35, v36, v37
	global_store_dwordx4 v38, v[32:35], s[14:15] nt
	v_pk_mul_f32 v[26:27], v[30:31], v[26:27]
	v_pk_mul_f32 v[24:25], v[28:29], v[24:25]
	v_pk_mul_f32 v[32:33], v[30:31], s[10:11] op_sel_hi:[1,0]
	v_pk_mul_f32 v[34:35], v[28:29], s[10:11] op_sel_hi:[1,0]
	v_pk_mul_f32 v[28:29], v[22:23], s[10:11] op_sel_hi:[1,0]
	v_pk_mul_f32 v[30:31], v[20:21], s[10:11] op_sel_hi:[1,0]
	v_exp_f32_e32 v28, v28
	v_exp_f32_e32 v30, v30
	v_exp_f32_e32 v29, v29
	v_exp_f32_e32 v31, v31
	v_exp_f32_e32 v34, v34
	v_exp_f32_e32 v32, v32
	v_exp_f32_e32 v33, v33
	v_exp_f32_e32 v35, v35
	v_pk_add_f32 v[28:29], v[28:29], 1.0 op_sel_hi:[1,0]
	v_pk_add_f32 v[30:31], v[30:31], 1.0 op_sel_hi:[1,0]
	v_pk_add_f32 v[32:33], v[32:33], 1.0 op_sel_hi:[1,0]
	v_pk_add_f32 v[34:35], v[34:35], 1.0 op_sel_hi:[1,0]
	v_rcp_f32_e32 v30, v30
	v_rcp_f32_e32 v28, v28
	v_rcp_f32_e32 v29, v29
	v_rcp_f32_e32 v31, v31
	v_rcp_f32_e32 v34, v34
	v_rcp_f32_e32 v35, v35
	v_rcp_f32_e32 v32, v32
	v_rcp_f32_e32 v33, v33
	v_pk_mul_f32 v[18:19], v[22:23], v[18:19]
	v_pk_mul_f32 v[16:17], v[20:21], v[16:17]
	v_pk_mul_f32 v[20:21], v[28:29], v[18:19]
	v_pk_mul_f32 v[18:19], v[30:31], v[16:17]
	v_pk_mul_f32 v[26:27], v[32:33], v[26:27]
	v_pk_mul_f32 v[24:25], v[34:35], v[24:25]
	v_add_u32_e32 v22, 0xdc000, v140
	v_cvt_pk_bf16_f32 v16, v24, v25
	v_cvt_pk_bf16_f32 v17, v26, v27
	v_cvt_pk_bf16_f32 v18, v18, v19
	v_cvt_pk_bf16_f32 v19, v20, v21
	global_store_dwordx4 v22, v[16:19], s[14:15] nt
	v_pk_mul_f32 v[10:11], v[14:15], v[10:11]
	v_pk_mul_f32 v[8:9], v[12:13], v[8:9]
	v_pk_mul_f32 v[16:17], v[14:15], s[10:11] op_sel_hi:[1,0]
	v_pk_mul_f32 v[18:19], v[12:13], s[10:11] op_sel_hi:[1,0]
	v_pk_mul_f32 v[12:13], v[6:7], s[10:11] op_sel_hi:[1,0]
	v_pk_mul_f32 v[14:15], v[4:5], s[10:11] op_sel_hi:[1,0]
	v_exp_f32_e32 v12, v12
	v_exp_f32_e32 v14, v14
	v_exp_f32_e32 v13, v13
	v_exp_f32_e32 v15, v15
	v_exp_f32_e32 v18, v18
	v_exp_f32_e32 v16, v16
	v_exp_f32_e32 v17, v17
	v_exp_f32_e32 v19, v19
	v_pk_add_f32 v[12:13], v[12:13], 1.0 op_sel_hi:[1,0]
	v_pk_add_f32 v[14:15], v[14:15], 1.0 op_sel_hi:[1,0]
	v_pk_add_f32 v[16:17], v[16:17], 1.0 op_sel_hi:[1,0]
	v_pk_add_f32 v[18:19], v[18:19], 1.0 op_sel_hi:[1,0]
	v_rcp_f32_e32 v14, v14
	v_rcp_f32_e32 v12, v12
	v_rcp_f32_e32 v13, v13
	v_rcp_f32_e32 v15, v15
	v_rcp_f32_e32 v18, v18
	v_rcp_f32_e32 v19, v19
	v_rcp_f32_e32 v16, v16
	v_rcp_f32_e32 v17, v17
	v_pk_mul_f32 v[2:3], v[6:7], v[2:3]
	v_pk_mul_f32 v[0:1], v[4:5], v[0:1]
	v_pk_mul_f32 v[4:5], v[12:13], v[2:3]
	v_pk_mul_f32 v[2:3], v[14:15], v[0:1]
	v_add_u32_e32 v6, 0xf2000, v140
	s_andn2_b64 vcc, exec, s[4:5]
	s_mov_b64 s[4:5], -1
	v_pk_mul_f32 v[10:11], v[16:17], v[10:11]
	v_pk_mul_f32 v[8:9], v[18:19], v[8:9]
	v_cvt_pk_bf16_f32 v1, v10, v11
	v_cvt_pk_bf16_f32 v2, v2, v3
	v_cvt_pk_bf16_f32 v3, v4, v5
	s_nop 0
	v_cvt_pk_bf16_f32 v0, v8, v9
	global_store_dwordx4 v6, v[0:3], s[14:15] nt
	s_cbranch_vccnz .LBB0_252
	s_andn2_b64 vcc, exec, s[0:1]
	s_cbranch_vccnz .LBB0_251
	s_barrier
	s_branch .LBB0_251

; __device__ __forceinline__ unsigned cvt_pk_bf16(float lo, float hi) { unsigned r; asm("v_cvt_pk_bf16_f32 %0, %1, %2" : "=v"(r) : "v"(lo), "v"(hi)); return r; }
;     __device__ __forceinline__ void operator()(const Acc& acc, const Unit& u, int wr, int wc, int fr, int fq) const {
;         const int row0 = u.pm * 256 + wr * 64 + fr, h0 = u.pn * 128 + wc * 32 + 8 * fq;
; #pragma unroll
;         for (int ai = 0; ai < 2; ++ai)
; #pragma unroll
;             for (int m = 0; m < 4; ++m) { bf16_t* rp = ACT + (size_t)(row0 + ai * 128 + m * 16) * FF + h0; float v[8];
; #pragma unroll
;                 for (int n = 0; n < 2; ++n) { const f32x4 a = acc[ai][0][m][n], b = acc[ai][1][m][n];
;                     const f32x4 t = a * (-LOG2E); f32x4 e; e.x = __builtin_amdgcn_exp2f(t.x); e.y = __builtin_amdgcn_exp2f(t.y); e.z = __builtin_amdgcn_exp2f(t.z); e.w = __builtin_amdgcn_exp2f(t.w);
;                     const f32x4 d = e + 1.0f; f32x4 r; r.x = __builtin_amdgcn_rcpf(d.x); r.y = __builtin_amdgcn_rcpf(d.y); r.z = __builtin_amdgcn_rcpf(d.z); r.w = __builtin_amdgcn_rcpf(d.w);
;                     const f32x4 o = (a * b) * r; v[4 * n + 0] = o.x; v[4 * n + 1] = o.y; v[4 * n + 2] = o.z; v[4 * n + 3] = o.w; }
;                 u32x4 w; w.x = cvt_pk_bf16(v[0], v[1]); w.y = cvt_pk_bf16(v[2], v[3]); w.z = cvt_pk_bf16(v[4], v[5]); w.w = cvt_pk_bf16(v[6], v[7]); __builtin_nontemporal_store(w, (u32x4*)rp); }
.LBB0_1047:
	v_pk_mul_f32 v[152:153], v[126:127], s[22:23] op_sel_hi:[1,0]
	v_pk_mul_f32 v[122:123], v[126:127], v[122:123]
	v_pk_mul_f32 v[126:127], v[116:117], s[22:23] op_sel_hi:[1,0]
	v_pk_mul_f32 v[154:155], v[124:125], s[22:23] op_sel_hi:[1,0]
	v_pk_mul_f32 v[120:121], v[124:125], v[120:121]
	v_pk_mul_f32 v[124:125], v[118:119], s[22:23] op_sel_hi:[1,0]
	v_exp_f32_e32 v126, v126
	v_exp_f32_e32 v127, v127
	v_exp_f32_e32 v154, v154
	v_exp_f32_e32 v152, v152
	v_exp_f32_e32 v153, v153
	v_exp_f32_e32 v155, v155
	v_exp_f32_e32 v124, v124
	v_exp_f32_e32 v125, v125
	v_pk_add_f32 v[126:127], v[126:127], 1.0 op_sel_hi:[1,0]
	v_pk_add_f32 v[152:153], v[152:153], 1.0 op_sel_hi:[1,0]
	v_pk_add_f32 v[154:155], v[154:155], 1.0 op_sel_hi:[1,0]
	v_pk_add_f32 v[124:125], v[124:125], 1.0 op_sel_hi:[1,0]
	v_rcp_f32_e32 v126, v126
	v_rcp_f32_e32 v127, v127
	v_rcp_f32_e32 v154, v154
	v_rcp_f32_e32 v155, v155
	v_rcp_f32_e32 v152, v152
	v_rcp_f32_e32 v153, v153
	v_rcp_f32_e32 v124, v124
	v_rcp_f32_e32 v125, v125
	v_lshl_or_b32 v150, s58, 7, v144
	v_lshl_add_u32 v148, s40, 8, v142
	v_pk_mul_f32 v[112:113], v[116:117], v[112:113]
	v_mul_u32_u24_e32 v140, s57, v148
	v_pk_mul_f32 v[114:115], v[118:119], v[114:115]
	v_pk_mul_f32 v[116:117], v[126:127], v[112:113]
	v_pk_mul_f32 v[122:123], v[152:153], v[122:123]
	v_pk_mul_f32 v[120:121], v[154:155], v[120:121]
	v_pk_mul_f32 v[118:119], v[124:125], v[114:115]
	v_lshl_add_u32 v140, v150, 1, v140
	v_cvt_pk_bf16_f32 v114, v120, v121
	v_cvt_pk_bf16_f32 v115, v122, v123
	v_cvt_pk_bf16_f32 v116, v116, v117
	v_cvt_pk_bf16_f32 v117, v118, v119
	global_store_dwordx4 v140, v[114:117], s[14:15] nt
	v_pk_mul_f32 v[106:107], v[110:111], v[106:107]
	v_pk_mul_f32 v[104:105], v[108:109], v[104:105]
	v_pk_mul_f32 v[114:115], v[110:111], s[22:23] op_sel_hi:[1,0]
	v_pk_mul_f32 v[116:117], v[108:109], s[22:23] op_sel_hi:[1,0]
	v_pk_mul_f32 v[108:109], v[102:103], s[22:23] op_sel_hi:[1,0]
	v_pk_mul_f32 v[110:111], v[100:101], s[22:23] op_sel_hi:[1,0]
	v_exp_f32_e32 v108, v108
	v_exp_f32_e32 v110, v110
	v_exp_f32_e32 v109, v109
	v_exp_f32_e32 v111, v111
	v_exp_f32_e32 v116, v116
	v_exp_f32_e32 v114, v114
	v_exp_f32_e32 v115, v115
	v_exp_f32_e32 v117, v117
	v_pk_add_f32 v[108:109], v[108:109], 1.0 op_sel_hi:[1,0]
	v_pk_add_f32 v[110:111], v[110:111], 1.0 op_sel_hi:[1,0]
	v_pk_add_f32 v[114:115], v[114:115], 1.0 op_sel_hi:[1,0]
	v_pk_add_f32 v[116:117], v[116:117], 1.0 op_sel_hi:[1,0]
	v_rcp_f32_e32 v110, v110
	v_rcp_f32_e32 v108, v108
	v_rcp_f32_e32 v109, v109
	v_rcp_f32_e32 v111, v111
	v_rcp_f32_e32 v116, v116
	v_rcp_f32_e32 v117, v117
	v_rcp_f32_e32 v114, v114
	v_rcp_f32_e32 v115, v115
	v_pk_mul_f32 v[98:99], v[102:103], v[98:99]
	v_pk_mul_f32 v[96:97], v[100:101], v[96:97]
	v_pk_mul_f32 v[100:101], v[108:109], v[98:99]
	v_pk_mul_f32 v[98:99], v[110:111], v[96:97]
	v_pk_mul_f32 v[106:107], v[114:115], v[106:107]
	v_pk_mul_f32 v[104:105], v[116:117], v[104:105]
	v_add_u32_e32 v102, 0x16000, v140
	v_cvt_pk_bf16_f32 v96, v104, v105
	v_cvt_pk_bf16_f32 v97, v106, v107
	v_cvt_pk_bf16_f32 v98, v98, v99
	v_cvt_pk_bf16_f32 v99, v100, v101
	global_store_dwordx4 v102, v[96:99], s[14:15] nt
	v_pk_mul_f32 v[90:91], v[94:95], v[90:91]
	v_pk_mul_f32 v[88:89], v[92:93], v[88:89]
	v_pk_mul_f32 v[96:97], v[94:95], s[22:23] op_sel_hi:[1,0]
	v_pk_mul_f32 v[98:99], v[92:93], s[22:23] op_sel_hi:[1,0]
	v_pk_mul_f32 v[92:93], v[86:87], s[22:23] op_sel_hi:[1,0]
	v_pk_mul_f32 v[94:95], v[84:85], s[22:23] op_sel_hi:[1,0]
	v_exp_f32_e32 v92, v92
	v_exp_f32_e32 v94, v94
	v_exp_f32_e32 v93, v93
	v_exp_f32_e32 v95, v95
	v_exp_f32_e32 v98, v98
	v_exp_f32_e32 v96, v96
	v_exp_f32_e32 v97, v97
	v_exp_f32_e32 v99, v99
	v_pk_add_f32 v[92:93], v[92:93], 1.0 op_sel_hi:[1,0]
	v_pk_add_f32 v[94:95], v[94:95], 1.0 op_sel_hi:[1,0]
	v_pk_add_f32 v[96:97], v[96:97], 1.0 op_sel_hi:[1,0]
	v_pk_add_f32 v[98:99], v[98:99], 1.0 op_sel_hi:[1,0]
	v_rcp_f32_e32 v94, v94
	v_rcp_f32_e32 v92, v92
	v_rcp_f32_e32 v93, v93
	v_rcp_f32_e32 v95, v95
	v_rcp_f32_e32 v98, v98
	v_rcp_f32_e32 v99, v99
	v_rcp_f32_e32 v96, v96
	v_rcp_f32_e32 v97, v97
	v_pk_mul_f32 v[82:83], v[86:87], v[82:83]
	v_pk_mul_f32 v[80:81], v[84:85], v[80:81]
	v_pk_mul_f32 v[84:85], v[92:93], v[82:83]
	v_pk_mul_f32 v[82:83], v[94:95], v[80:81]
	v_pk_mul_f32 v[90:91], v[96:97], v[90:91]
	v_pk_mul_f32 v[88:89], v[98:99], v[88:89]
	v_add_u32_e32 v86, 0x2c000, v140
	v_cvt_pk_bf16_f32 v80, v88, v89
	v_cvt_pk_bf16_f32 v81, v90, v91
	v_cvt_pk_bf16_f32 v82, v82, v83
	v_cvt_pk_bf16_f32 v83, v84, v85
	global_store_dwordx4 v86, v[80:83], s[14:15] nt
	v_pk_mul_f32 v[74:75], v[78:79], v[74:75]
	v_pk_mul_f32 v[72:73], v[76:77], v[72:73]
	v_pk_mul_f32 v[80:81], v[78:79], s[22:23] op_sel_hi:[1,0]
	v_pk_mul_f32 v[82:83], v[76:77], s[22:23] op_sel_hi:[1,0]
	v_pk_mul_f32 v[76:77], v[70:71], s[22:23] op_sel_hi:[1,0]
	v_pk_mul_f32 v[78:79], v[68:69], s[22:23] op_sel_hi:[1,0]
	v_exp_f32_e32 v76, v76
	v_exp_f32_e32 v78, v78
	v_exp_f32_e32 v77, v77
	v_exp_f32_e32 v79, v79
	v_exp_f32_e32 v82, v82
	v_exp_f32_e32 v80, v80
	v_exp_f32_e32 v81, v81
	v_exp_f32_e32 v83, v83
	v_pk_add_f32 v[76:77], v[76:77], 1.0 op_sel_hi:[1,0]
	v_pk_add_f32 v[78:79], v[78:79], 1.0 op_sel_hi:[1,0]
	v_pk_add_f32 v[80:81], v[80:81], 1.0 op_sel_hi:[1,0]
	v_pk_add_f32 v[82:83], v[82:83], 1.0 op_sel_hi:[1,0]
	v_rcp_f32_e32 v78, v78
	v_rcp_f32_e32 v76, v76
	v_rcp_f32_e32 v77, v77
	v_rcp_f32_e32 v79, v79
	v_rcp_f32_e32 v82, v82
	v_rcp_f32_e32 v83, v83
	v_rcp_f32_e32 v80, v80
	v_rcp_f32_e32 v81, v81
	v_pk_mul_f32 v[66:67], v[70:71], v[66:67]
	v_pk_mul_f32 v[64:65], v[68:69], v[64:65]
	v_pk_mul_f32 v[68:69], v[76:77], v[66:67]
	v_pk_mul_f32 v[66:67], v[78:79], v[64:65]
; __device__ __forceinline__ unsigned cvt_pk_bf16(float lo, float hi) { unsigned r; asm("v_cvt_pk_bf16_f32 %0, %1, %2" : "=v"(r) : "v"(lo), "v"(hi)); return r; }
;     __device__ __forceinline__ void operator()(const Acc& acc, const Unit& u, int wr, int wc, int fr, int fq) const {
;         const int row0 = u.pm * 256 + wr * 64 + fr, h0 = u.pn * 128 + wc * 32 + 8 * fq;
; #pragma unroll
;         for (int ai = 0; ai < 2; ++ai)
; #pragma unroll
;             for (int m = 0; m < 4; ++m) { bf16_t* rp = ACT + (size_t)(row0 + ai * 128 + m * 16) * FF + h0; float v[8];
; #pragma unroll
;                 for (int n = 0; n < 2; ++n) { const f32x4 a = acc[ai][0][m][n], b = acc[ai][1][m][n];
;                     const f32x4 t = a * (-LOG2E); f32x4 e; e.x = __builtin_amdgcn_exp2f(t.x); e.y = __builtin_amdgcn_exp2f(t.y); e.z = __builtin_amdgcn_exp2f(t.z); e.w = __builtin_amdgcn_exp2f(t.w);
;                     const f32x4 d = e + 1.0f; f32x4 r; r.x = __builtin_amdgcn_rcpf(d.x); r.y = __builtin_amdgcn_rcpf(d.y); r.z = __builtin_amdgcn_rcpf(d.z); r.w = __builtin_amdgcn_rcpf(d.w);
;                     const f32x4 o = (a * b) * r; v[4 * n + 0] = o.x; v[4 * n + 1] = o.y; v[4 * n + 2] = o.z; v[4 * n + 3] = o.w; }
;                 u32x4 w; w.x = cvt_pk_bf16(v[0], v[1]); w.y = cvt_pk_bf16(v[2], v[3]); w.z = cvt_pk_bf16(v[4], v[5]); w.w = cvt_pk_bf16(v[6], v[7]); __builtin_nontemporal_store(w, (u32x4*)rp); }
	v_pk_mul_f32 v[74:75], v[80:81], v[74:75]
	v_pk_mul_f32 v[72:73], v[82:83], v[72:73]
	v_add_u32_e32 v70, 0x42000, v140
	v_cvt_pk_bf16_f32 v64, v72, v73
	v_cvt_pk_bf16_f32 v65, v74, v75
	v_cvt_pk_bf16_f32 v66, v66, v67
	v_cvt_pk_bf16_f32 v67, v68, v69
	global_store_dwordx4 v70, v[64:67], s[14:15] nt
	v_pk_mul_f32 v[58:59], v[62:63], v[58:59]
	v_pk_mul_f32 v[56:57], v[60:61], v[56:57]
	v_pk_mul_f32 v[64:65], v[62:63], s[22:23] op_sel_hi:[1,0]
	v_pk_mul_f32 v[66:67], v[60:61], s[22:23] op_sel_hi:[1,0]
	v_pk_mul_f32 v[60:61], v[54:55], s[22:23] op_sel_hi:[1,0]
	v_pk_mul_f32 v[62:63], v[52:53], s[22:23] op_sel_hi:[1,0]
	v_exp_f32_e32 v60, v60
	v_exp_f32_e32 v62, v62
	v_exp_f32_e32 v61, v61
	v_exp_f32_e32 v63, v63
	v_exp_f32_e32 v66, v66
	v_exp_f32_e32 v64, v64
	v_exp_f32_e32 v65, v65
	v_exp_f32_e32 v67, v67
	v_pk_add_f32 v[60:61], v[60:61], 1.0 op_sel_hi:[1,0]
	v_pk_add_f32 v[62:63], v[62:63], 1.0 op_sel_hi:[1,0]
	v_pk_add_f32 v[64:65], v[64:65], 1.0 op_sel_hi:[1,0]
	v_pk_add_f32 v[66:67], v[66:67], 1.0 op_sel_hi:[1,0]
	v_rcp_f32_e32 v62, v62
	v_rcp_f32_e32 v60, v60
	v_rcp_f32_e32 v61, v61
	v_rcp_f32_e32 v63, v63
	v_rcp_f32_e32 v66, v66
	v_rcp_f32_e32 v67, v67
	v_rcp_f32_e32 v64, v64
	v_rcp_f32_e32 v65, v65
	v_pk_mul_f32 v[50:51], v[54:55], v[50:51]
	v_pk_mul_f32 v[48:49], v[52:53], v[48:49]
	v_pk_mul_f32 v[52:53], v[60:61], v[50:51]
	v_pk_mul_f32 v[50:51], v[62:63], v[48:49]
	v_pk_mul_f32 v[58:59], v[64:65], v[58:59]
	v_pk_mul_f32 v[56:57], v[66:67], v[56:57]
	v_add_u32_e32 v54, 0xb0000, v140
	v_cvt_pk_bf16_f32 v48, v56, v57
	v_cvt_pk_bf16_f32 v49, v58, v59
	v_cvt_pk_bf16_f32 v50, v50, v51
	v_cvt_pk_bf16_f32 v51, v52, v53
	global_store_dwordx4 v54, v[48:51], s[14:15] nt
	v_pk_mul_f32 v[42:43], v[46:47], v[42:43]
	v_pk_mul_f32 v[40:41], v[44:45], v[40:41]
	v_pk_mul_f32 v[48:49], v[46:47], s[22:23] op_sel_hi:[1,0]
	v_pk_mul_f32 v[50:51], v[44:45], s[22:23] op_sel_hi:[1,0]
	v_pk_mul_f32 v[44:45], v[38:39], s[22:23] op_sel_hi:[1,0]
	v_pk_mul_f32 v[46:47], v[36:37], s[22:23] op_sel_hi:[1,0]
	v_exp_f32_e32 v44, v44
	v_exp_f32_e32 v46, v46
	v_exp_f32_e32 v45, v45
	v_exp_f32_e32 v47, v47
	v_exp_f32_e32 v50, v50
	v_exp_f32_e32 v48, v48
	v_exp_f32_e32 v49, v49
	v_exp_f32_e32 v51, v51
	v_pk_add_f32 v[44:45], v[44:45], 1.0 op_sel_hi:[1,0]
	v_pk_add_f32 v[46:47], v[46:47], 1.0 op_sel_hi:[1,0]
	v_pk_add_f32 v[48:49], v[48:49], 1.0 op_sel_hi:[1,0]
	v_pk_add_f32 v[50:51], v[50:51], 1.0 op_sel_hi:[1,0]
	v_rcp_f32_e32 v46, v46
	v_rcp_f32_e32 v44, v44
	v_rcp_f32_e32 v45, v45
	v_rcp_f32_e32 v47, v47
	v_rcp_f32_e32 v50, v50
	v_rcp_f32_e32 v51, v51
	v_rcp_f32_e32 v48, v48
	v_rcp_f32_e32 v49, v49
	v_pk_mul_f32 v[34:35], v[38:39], v[34:35]
	v_pk_mul_f32 v[32:33], v[36:37], v[32:33]
	v_pk_mul_f32 v[36:37], v[44:45], v[34:35]
	v_pk_mul_f32 v[34:35], v[46:47], v[32:33]
	v_pk_mul_f32 v[42:43], v[48:49], v[42:43]
	v_pk_mul_f32 v[40:41], v[50:51], v[40:41]
	v_add_u32_e32 v38, 0xc6000, v140
	v_cvt_pk_bf16_f32 v32, v40, v41
	v_cvt_pk_bf16_f32 v33, v42, v43
	v_cvt_pk_bf16_f32 v34, v34, v35
	v_cvt_pk_bf16_f32 v35, v36, v37
	global_store_dwordx4 v38, v[32:35], s[14:15] nt
	v_pk_mul_f32 v[26:27], v[30:31], v[26:27]
	v_pk_mul_f32 v[24:25], v[28:29], v[24:25]
	v_pk_mul_f32 v[32:33], v[30:31], s[22:23] op_sel_hi:[1,0]
	v_pk_mul_f32 v[34:35], v[28:29], s[22:23] op_sel_hi:[1,0]
	v_pk_mul_f32 v[28:29], v[22:23], s[22:23] op_sel_hi:[1,0]
	v_pk_mul_f32 v[30:31], v[20:21], s[22:23] op_sel_hi:[1,0]
	v_exp_f32_e32 v28, v28
	v_exp_f32_e32 v30, v30
	v_exp_f32_e32 v29, v29
	v_exp_f32_e32 v31, v31
	v_exp_f32_e32 v34, v34
	v_exp_f32_e32 v32, v32
	v_exp_f32_e32 v33, v33
	v_exp_f32_e32 v35, v35
	v_pk_add_f32 v[28:29], v[28:29], 1.0 op_sel_hi:[1,0]
	v_pk_add_f32 v[30:31], v[30:31], 1.0 op_sel_hi:[1,0]
	v_pk_add_f32 v[32:33], v[32:33], 1.0 op_sel_hi:[1,0]
	v_pk_add_f32 v[34:35], v[34:35], 1.0 op_sel_hi:[1,0]
	v_rcp_f32_e32 v30, v30
	v_rcp_f32_e32 v28, v28
	v_rcp_f32_e32 v29, v29
	v_rcp_f32_e32 v31, v31
	v_rcp_f32_e32 v34, v34
	v_rcp_f32_e32 v35, v35
	v_rcp_f32_e32 v32, v32
	v_rcp_f32_e32 v33, v33
	v_pk_mul_f32 v[18:19], v[22:23], v[18:19]
	v_pk_mul_f32 v[16:17], v[20:21], v[16:17]
	v_pk_mul_f32 v[20:21], v[28:29], v[18:19]
	v_pk_mul_f32 v[18:19], v[30:31], v[16:17]
	v_pk_mul_f32 v[26:27], v[32:33], v[26:27]
	v_pk_mul_f32 v[24:25], v[34:35], v[24:25]
	v_add_u32_e32 v22, 0xdc000, v140
	v_cvt_pk_bf16_f32 v16, v24, v25
	v_cvt_pk_bf16_f32 v17, v26, v27
	v_cvt_pk_bf16_f32 v18, v18, v19
	v_cvt_pk_bf16_f32 v19, v20, v21
	global_store_dwordx4 v22, v[16:19], s[14:15] nt
	v_pk_mul_f32 v[10:11], v[14:15], v[10:11]
	v_pk_mul_f32 v[8:9], v[12:13], v[8:9]
	v_pk_mul_f32 v[16:17], v[14:15], s[22:23] op_sel_hi:[1,0]
	v_pk_mul_f32 v[18:19], v[12:13], s[22:23] op_sel_hi:[1,0]
	v_pk_mul_f32 v[12:13], v[6:7], s[22:23] op_sel_hi:[1,0]
	v_pk_mul_f32 v[14:15], v[4:5], s[22:23] op_sel_hi:[1,0]
	v_exp_f32_e32 v12, v12
	v_exp_f32_e32 v14, v14
	v_exp_f32_e32 v13, v13
	v_exp_f32_e32 v15, v15
	v_exp_f32_e32 v18, v18
	v_exp_f32_e32 v16, v16
	v_exp_f32_e32 v17, v17
	v_exp_f32_e32 v19, v19
	v_pk_add_f32 v[12:13], v[12:13], 1.0 op_sel_hi:[1,0]
	v_pk_add_f32 v[14:15], v[14:15], 1.0 op_sel_hi:[1,0]
	v_pk_add_f32 v[16:17], v[16:17], 1.0 op_sel_hi:[1,0]
	v_pk_add_f32 v[18:19], v[18:19], 1.0 op_sel_hi:[1,0]
	v_rcp_f32_e32 v14, v14
	v_rcp_f32_e32 v12, v12
	v_rcp_f32_e32 v13, v13
	v_rcp_f32_e32 v15, v15
	v_rcp_f32_e32 v18, v18
	v_rcp_f32_e32 v19, v19
	v_rcp_f32_e32 v16, v16
	v_rcp_f32_e32 v17, v17
	v_pk_mul_f32 v[2:3], v[6:7], v[2:3]
	v_pk_mul_f32 v[0:1], v[4:5], v[0:1]
	v_pk_mul_f32 v[4:5], v[12:13], v[2:3]
	v_pk_mul_f32 v[2:3], v[14:15], v[0:1]
	v_add_u32_e32 v6, 0xf2000, v140
	s_andn2_b64 vcc, exec, s[4:5]
	s_mov_b64 s[4:5], -1
	v_pk_mul_f32 v[10:11], v[16:17], v[10:11]
	v_pk_mul_f32 v[8:9], v[18:19], v[8:9]
	v_cvt_pk_bf16_f32 v1, v10, v11
	v_cvt_pk_bf16_f32 v2, v2, v3
	v_cvt_pk_bf16_f32 v3, v4, v5
	s_nop 0
	v_cvt_pk_bf16_f32 v0, v8, v9
	global_store_dwordx4 v6, v[0:3], s[14:15] nt
	s_cbranch_vccnz .LBB0_1040
	s_andn2_b64 vcc, exec, s[6:7]
	s_cbranch_vccnz .LBB0_1039
	s_barrier
	s_branch .LBB0_1039

; __device__ __forceinline__ unsigned cvt_pk_bf16(float lo, float hi) { unsigned r; asm("v_cvt_pk_bf16_f32 %0, %1, %2" : "=v"(r) : "v"(lo), "v"(hi)); return r; }
;     __device__ __forceinline__ void operator()(const Acc& acc, const Unit& u, int wr, int wc, int fr, int fq) const {
;         const int row0 = u.pm * 256 + wr * 64 + fr, h0 = u.pn * 128 + wc * 32 + 8 * fq;
; #pragma unroll
;         for (int ai = 0; ai < 2; ++ai)
; #pragma unroll
;             for (int m = 0; m < 4; ++m) { bf16_t* rp = ACT + (size_t)(row0 + ai * 128 + m * 16) * FF + h0; float v[8];
; #pragma unroll
;                 for (int n = 0; n < 2; ++n) { const f32x4 a = acc[ai][0][m][n], b = acc[ai][1][m][n];
;                     const f32x4 t = a * (-LOG2E); f32x4 e; e.x = __builtin_amdgcn_exp2f(t.x); e.y = __builtin_amdgcn_exp2f(t.y); e.z = __builtin_amdgcn_exp2f(t.z); e.w = __builtin_amdgcn_exp2f(t.w);
;                     const f32x4 d = e + 1.0f; f32x4 r; r.x = __builtin_amdgcn_rcpf(d.x); r.y = __builtin_amdgcn_rcpf(d.y); r.z = __builtin_amdgcn_rcpf(d.z); r.w = __builtin_amdgcn_rcpf(d.w);
;                     const f32x4 o = (a * b) * r; v[4 * n + 0] = o.x; v[4 * n + 1] = o.y; v[4 * n + 2] = o.z; v[4 * n + 3] = o.w; }
;                 u32x4 w; w.x = cvt_pk_bf16(v[0], v[1]); w.y = cvt_pk_bf16(v[2], v[3]); w.z = cvt_pk_bf16(v[4], v[5]); w.w = cvt_pk_bf16(v[6], v[7]); __builtin_nontemporal_store(w, (u32x4*)rp); }
.LBB0_1250:
	v_pk_mul_f32 v[152:153], v[126:127], s[22:23] op_sel_hi:[1,0]
	v_pk_mul_f32 v[122:123], v[126:127], v[122:123]
	v_pk_mul_f32 v[126:127], v[116:117], s[22:23] op_sel_hi:[1,0]
	v_pk_mul_f32 v[154:155], v[124:125], s[22:23] op_sel_hi:[1,0]
	v_pk_mul_f32 v[120:121], v[124:125], v[120:121]
	v_pk_mul_f32 v[124:125], v[118:119], s[22:23] op_sel_hi:[1,0]
	v_exp_f32_e32 v126, v126
	v_exp_f32_e32 v127, v127
	v_exp_f32_e32 v154, v154
	v_exp_f32_e32 v152, v152
	v_exp_f32_e32 v153, v153
	v_exp_f32_e32 v155, v155
	v_exp_f32_e32 v124, v124
	v_exp_f32_e32 v125, v125
	v_pk_add_f32 v[126:127], v[126:127], 1.0 op_sel_hi:[1,0]
	v_pk_add_f32 v[152:153], v[152:153], 1.0 op_sel_hi:[1,0]
	v_pk_add_f32 v[154:155], v[154:155], 1.0 op_sel_hi:[1,0]
	v_pk_add_f32 v[124:125], v[124:125], 1.0 op_sel_hi:[1,0]
	v_rcp_f32_e32 v126, v126
	v_rcp_f32_e32 v127, v127
	v_rcp_f32_e32 v154, v154
	v_rcp_f32_e32 v155, v155
	v_rcp_f32_e32 v152, v152
	v_rcp_f32_e32 v153, v153
	v_rcp_f32_e32 v124, v124
	v_rcp_f32_e32 v125, v125
	v_lshl_or_b32 v150, s58, 7, v144
	v_lshl_add_u32 v148, s40, 8, v142
	v_pk_mul_f32 v[112:113], v[116:117], v[112:113]
	v_mul_u32_u24_e32 v140, s57, v148
	v_pk_mul_f32 v[114:115], v[118:119], v[114:115]
	v_pk_mul_f32 v[116:117], v[126:127], v[112:113]
	v_pk_mul_f32 v[122:123], v[152:153], v[122:123]
	v_pk_mul_f32 v[120:121], v[154:155], v[120:121]
	v_pk_mul_f32 v[118:119], v[124:125], v[114:115]
	v_lshl_add_u32 v140, v150, 1, v140
	v_cvt_pk_bf16_f32 v114, v120, v121
	v_cvt_pk_bf16_f32 v115, v122, v123
	v_cvt_pk_bf16_f32 v116, v116, v117
	v_cvt_pk_bf16_f32 v117, v118, v119
	global_store_dwordx4 v140, v[114:117], s[14:15] nt
	v_pk_mul_f32 v[106:107], v[110:111], v[106:107]
	v_pk_mul_f32 v[104:105], v[108:109], v[104:105]
	v_pk_mul_f32 v[114:115], v[110:111], s[22:23] op_sel_hi:[1,0]
	v_pk_mul_f32 v[116:117], v[108:109], s[22:23] op_sel_hi:[1,0]
	v_pk_mul_f32 v[108:109], v[102:103], s[22:23] op_sel_hi:[1,0]
	v_pk_mul_f32 v[110:111], v[100:101], s[22:23] op_sel_hi:[1,0]
	v_exp_f32_e32 v108, v108
	v_exp_f32_e32 v110, v110
	v_exp_f32_e32 v109, v109
	v_exp_f32_e32 v111, v111
	v_exp_f32_e32 v116, v116
	v_exp_f32_e32 v114, v114
	v_exp_f32_e32 v115, v115
	v_exp_f32_e32 v117, v117
	v_pk_add_f32 v[108:109], v[108:109], 1.0 op_sel_hi:[1,0]
	v_pk_add_f32 v[110:111], v[110:111], 1.0 op_sel_hi:[1,0]
	v_pk_add_f32 v[114:115], v[114:115], 1.0 op_sel_hi:[1,0]
	v_pk_add_f32 v[116:117], v[116:117], 1.0 op_sel_hi:[1,0]
	v_rcp_f32_e32 v110, v110
	v_rcp_f32_e32 v108, v108
	v_rcp_f32_e32 v109, v109
	v_rcp_f32_e32 v111, v111
	v_rcp_f32_e32 v116, v116
	v_rcp_f32_e32 v117, v117
	v_rcp_f32_e32 v114, v114
	v_rcp_f32_e32 v115, v115
	v_pk_mul_f32 v[98:99], v[102:103], v[98:99]
	v_pk_mul_f32 v[96:97], v[100:101], v[96:97]
	v_pk_mul_f32 v[100:101], v[108:109], v[98:99]
	v_pk_mul_f32 v[98:99], v[110:111], v[96:97]
	v_pk_mul_f32 v[106:107], v[114:115], v[106:107]
	v_pk_mul_f32 v[104:105], v[116:117], v[104:105]
	v_add_u32_e32 v102, 0x16000, v140
	v_cvt_pk_bf16_f32 v96, v104, v105
	v_cvt_pk_bf16_f32 v97, v106, v107
	v_cvt_pk_bf16_f32 v98, v98, v99
	v_cvt_pk_bf16_f32 v99, v100, v101
	global_store_dwordx4 v102, v[96:99], s[14:15] nt
	v_pk_mul_f32 v[90:91], v[94:95], v[90:91]
	v_pk_mul_f32 v[88:89], v[92:93], v[88:89]
	v_pk_mul_f32 v[96:97], v[94:95], s[22:23] op_sel_hi:[1,0]
	v_pk_mul_f32 v[98:99], v[92:93], s[22:23] op_sel_hi:[1,0]
	v_pk_mul_f32 v[92:93], v[86:87], s[22:23] op_sel_hi:[1,0]
	v_pk_mul_f32 v[94:95], v[84:85], s[22:23] op_sel_hi:[1,0]
	v_exp_f32_e32 v92, v92
	v_exp_f32_e32 v94, v94
	v_exp_f32_e32 v93, v93
	v_exp_f32_e32 v95, v95
	v_exp_f32_e32 v98, v98
	v_exp_f32_e32 v96, v96
	v_exp_f32_e32 v97, v97
	v_exp_f32_e32 v99, v99
	v_pk_add_f32 v[92:93], v[92:93], 1.0 op_sel_hi:[1,0]
	v_pk_add_f32 v[94:95], v[94:95], 1.0 op_sel_hi:[1,0]
	v_pk_add_f32 v[96:97], v[96:97], 1.0 op_sel_hi:[1,0]
	v_pk_add_f32 v[98:99], v[98:99], 1.0 op_sel_hi:[1,0]
	v_rcp_f32_e32 v94, v94
	v_rcp_f32_e32 v92, v92
	v_rcp_f32_e32 v93, v93
	v_rcp_f32_e32 v95, v95
	v_rcp_f32_e32 v98, v98
	v_rcp_f32_e32 v99, v99
	v_rcp_f32_e32 v96, v96
	v_rcp_f32_e32 v97, v97
	v_pk_mul_f32 v[82:83], v[86:87], v[82:83]
	v_pk_mul_f32 v[80:81], v[84:85], v[80:81]
	v_pk_mul_f32 v[84:85], v[92:93], v[82:83]
	v_pk_mul_f32 v[82:83], v[94:95], v[80:81]
	v_pk_mul_f32 v[90:91], v[96:97], v[90:91]
	v_pk_mul_f32 v[88:89], v[98:99], v[88:89]
	v_add_u32_e32 v86, 0x2c000, v140
	v_cvt_pk_bf16_f32 v80, v88, v89
	v_cvt_pk_bf16_f32 v81, v90, v91
	v_cvt_pk_bf16_f32 v82, v82, v83
	v_cvt_pk_bf16_f32 v83, v84, v85
	global_store_dwordx4 v86, v[80:83], s[14:15] nt
	v_pk_mul_f32 v[74:75], v[78:79], v[74:75]
	v_pk_mul_f32 v[72:73], v[76:77], v[72:73]
	v_pk_mul_f32 v[80:81], v[78:79], s[22:23] op_sel_hi:[1,0]
	v_pk_mul_f32 v[82:83], v[76:77], s[22:23] op_sel_hi:[1,0]
	v_pk_mul_f32 v[76:77], v[70:71], s[22:23] op_sel_hi:[1,0]
	v_pk_mul_f32 v[78:79], v[68:69], s[22:23] op_sel_hi:[1,0]
	v_exp_f32_e32 v76, v76
	v_exp_f32_e32 v78, v78
	v_exp_f32_e32 v77, v77
	v_exp_f32_e32 v79, v79
	v_exp_f32_e32 v82, v82
	v_exp_f32_e32 v80, v80
	v_exp_f32_e32 v81, v81
	v_exp_f32_e32 v83, v83
	v_pk_add_f32 v[76:77], v[76:77], 1.0 op_sel_hi:[1,0]
	v_pk_add_f32 v[78:79], v[78:79], 1.0 op_sel_hi:[1,0]
	v_pk_add_f32 v[80:81], v[80:81], 1.0 op_sel_hi:[1,0]
	v_pk_add_f32 v[82:83], v[82:83], 1.0 op_sel_hi:[1,0]
	v_rcp_f32_e32 v78, v78
	v_rcp_f32_e32 v76, v76
	v_rcp_f32_e32 v77, v77
	v_rcp_f32_e32 v79, v79
	v_rcp_f32_e32 v82, v82
	v_rcp_f32_e32 v83, v83
	v_rcp_f32_e32 v80, v80
	v_rcp_f32_e32 v81, v81
	v_pk_mul_f32 v[66:67], v[70:71], v[66:67]
	v_pk_mul_f32 v[64:65], v[68:69], v[64:65]
	v_pk_mul_f32 v[68:69], v[76:77], v[66:67]
	v_pk_mul_f32 v[66:67], v[78:79], v[64:65]
; __device__ __forceinline__ unsigned cvt_pk_bf16(float lo, float hi) { unsigned r; asm("v_cvt_pk_bf16_f32 %0, %1, %2" : "=v"(r) : "v"(lo), "v"(hi)); return r; }
;     __device__ __forceinline__ void operator()(const Acc& acc, const Unit& u, int wr, int wc, int fr, int fq) const {
;         const int row0 = u.pm * 256 + wr * 64 + fr, h0 = u.pn * 128 + wc * 32 + 8 * fq;
; #pragma unroll
;         for (int ai = 0; ai < 2; ++ai)
; #pragma unroll
;             for (int m = 0; m < 4; ++m) { bf16_t* rp = ACT + (size_t)(row0 + ai * 128 + m * 16) * FF + h0; float v[8];
; #pragma unroll
;                 for (int n = 0; n < 2; ++n) { const f32x4 a = acc[ai][0][m][n], b = acc[ai][1][m][n];
;                     const f32x4 t = a * (-LOG2E); f32x4 e; e.x = __builtin_amdgcn_exp2f(t.x); e.y = __builtin_amdgcn_exp2f(t.y); e.z = __builtin_amdgcn_exp2f(t.z); e.w = __builtin_amdgcn_exp2f(t.w);
;                     const f32x4 d = e + 1.0f; f32x4 r; r.x = __builtin_amdgcn_rcpf(d.x); r.y = __builtin_amdgcn_rcpf(d.y); r.z = __builtin_amdgcn_rcpf(d.z); r.w = __builtin_amdgcn_rcpf(d.w);
;                     const f32x4 o = (a * b) * r; v[4 * n + 0] = o.x; v[4 * n + 1] = o.y; v[4 * n + 2] = o.z; v[4 * n + 3] = o.w; }
;                 u32x4 w; w.x = cvt_pk_bf16(v[0], v[1]); w.y = cvt_pk_bf16(v[2], v[3]); w.z = cvt_pk_bf16(v[4], v[5]); w.w = cvt_pk_bf16(v[6], v[7]); __builtin_nontemporal_store(w, (u32x4*)rp); }
	v_pk_mul_f32 v[74:75], v[80:81], v[74:75]
	v_pk_mul_f32 v[72:73], v[82:83], v[72:73]
	v_add_u32_e32 v70, 0x42000, v140
	v_cvt_pk_bf16_f32 v64, v72, v73
	v_cvt_pk_bf16_f32 v65, v74, v75
	v_cvt_pk_bf16_f32 v66, v66, v67
	v_cvt_pk_bf16_f32 v67, v68, v69
	global_store_dwordx4 v70, v[64:67], s[14:15] nt
	v_pk_mul_f32 v[58:59], v[62:63], v[58:59]
	v_pk_mul_f32 v[56:57], v[60:61], v[56:57]
	v_pk_mul_f32 v[64:65], v[62:63], s[22:23] op_sel_hi:[1,0]
	v_pk_mul_f32 v[66:67], v[60:61], s[22:23] op_sel_hi:[1,0]
	v_pk_mul_f32 v[60:61], v[54:55], s[22:23] op_sel_hi:[1,0]
	v_pk_mul_f32 v[62:63], v[52:53], s[22:23] op_sel_hi:[1,0]
	v_exp_f32_e32 v60, v60
	v_exp_f32_e32 v62, v62
	v_exp_f32_e32 v61, v61
	v_exp_f32_e32 v63, v63
	v_exp_f32_e32 v66, v66
	v_exp_f32_e32 v64, v64
	v_exp_f32_e32 v65, v65
	v_exp_f32_e32 v67, v67
	v_pk_add_f32 v[60:61], v[60:61], 1.0 op_sel_hi:[1,0]
	v_pk_add_f32 v[62:63], v[62:63], 1.0 op_sel_hi:[1,0]
	v_pk_add_f32 v[64:65], v[64:65], 1.0 op_sel_hi:[1,0]
	v_pk_add_f32 v[66:67], v[66:67], 1.0 op_sel_hi:[1,0]
	v_rcp_f32_e32 v62, v62
	v_rcp_f32_e32 v60, v60
	v_rcp_f32_e32 v61, v61
	v_rcp_f32_e32 v63, v63
	v_rcp_f32_e32 v66, v66
	v_rcp_f32_e32 v67, v67
	v_rcp_f32_e32 v64, v64
	v_rcp_f32_e32 v65, v65
	v_pk_mul_f32 v[50:51], v[54:55], v[50:51]
	v_pk_mul_f32 v[48:49], v[52:53], v[48:49]
	v_pk_mul_f32 v[52:53], v[60:61], v[50:51]
	v_pk_mul_f32 v[50:51], v[62:63], v[48:49]
	v_pk_mul_f32 v[58:59], v[64:65], v[58:59]
	v_pk_mul_f32 v[56:57], v[66:67], v[56:57]
	v_add_u32_e32 v54, 0xb0000, v140
	v_cvt_pk_bf16_f32 v48, v56, v57
	v_cvt_pk_bf16_f32 v49, v58, v59
	v_cvt_pk_bf16_f32 v50, v50, v51
	v_cvt_pk_bf16_f32 v51, v52, v53
	global_store_dwordx4 v54, v[48:51], s[14:15] nt
	v_pk_mul_f32 v[42:43], v[46:47], v[42:43]
	v_pk_mul_f32 v[40:41], v[44:45], v[40:41]
	v_pk_mul_f32 v[48:49], v[46:47], s[22:23] op_sel_hi:[1,0]
	v_pk_mul_f32 v[50:51], v[44:45], s[22:23] op_sel_hi:[1,0]
	v_pk_mul_f32 v[44:45], v[38:39], s[22:23] op_sel_hi:[1,0]
	v_pk_mul_f32 v[46:47], v[36:37], s[22:23] op_sel_hi:[1,0]
	v_exp_f32_e32 v44, v44
	v_exp_f32_e32 v46, v46
	v_exp_f32_e32 v45, v45
	v_exp_f32_e32 v47, v47
	v_exp_f32_e32 v50, v50
	v_exp_f32_e32 v48, v48
	v_exp_f32_e32 v49, v49
	v_exp_f32_e32 v51, v51
	v_pk_add_f32 v[44:45], v[44:45], 1.0 op_sel_hi:[1,0]
	v_pk_add_f32 v[46:47], v[46:47], 1.0 op_sel_hi:[1,0]
	v_pk_add_f32 v[48:49], v[48:49], 1.0 op_sel_hi:[1,0]
	v_pk_add_f32 v[50:51], v[50:51], 1.0 op_sel_hi:[1,0]
	v_rcp_f32_e32 v46, v46
	v_rcp_f32_e32 v44, v44
	v_rcp_f32_e32 v45, v45
	v_rcp_f32_e32 v47, v47
	v_rcp_f32_e32 v50, v50
	v_rcp_f32_e32 v51, v51
	v_rcp_f32_e32 v48, v48
	v_rcp_f32_e32 v49, v49
	v_pk_mul_f32 v[34:35], v[38:39], v[34:35]
	v_pk_mul_f32 v[32:33], v[36:37], v[32:33]
	v_pk_mul_f32 v[36:37], v[44:45], v[34:35]
	v_pk_mul_f32 v[34:35], v[46:47], v[32:33]
	v_pk_mul_f32 v[42:43], v[48:49], v[42:43]
	v_pk_mul_f32 v[40:41], v[50:51], v[40:41]
	v_add_u32_e32 v38, 0xc6000, v140
	v_cvt_pk_bf16_f32 v32, v40, v41
	v_cvt_pk_bf16_f32 v33, v42, v43
	v_cvt_pk_bf16_f32 v34, v34, v35
	v_cvt_pk_bf16_f32 v35, v36, v37
	global_store_dwordx4 v38, v[32:35], s[14:15] nt
	v_pk_mul_f32 v[26:27], v[30:31], v[26:27]
	v_pk_mul_f32 v[24:25], v[28:29], v[24:25]
	v_pk_mul_f32 v[32:33], v[30:31], s[22:23] op_sel_hi:[1,0]
	v_pk_mul_f32 v[34:35], v[28:29], s[22:23] op_sel_hi:[1,0]
	v_pk_mul_f32 v[28:29], v[22:23], s[22:23] op_sel_hi:[1,0]
	v_pk_mul_f32 v[30:31], v[20:21], s[22:23] op_sel_hi:[1,0]
	v_exp_f32_e32 v28, v28
	v_exp_f32_e32 v30, v30
	v_exp_f32_e32 v29, v29
	v_exp_f32_e32 v31, v31
	v_exp_f32_e32 v34, v34
	v_exp_f32_e32 v32, v32
	v_exp_f32_e32 v33, v33
	v_exp_f32_e32 v35, v35
	v_pk_add_f32 v[28:29], v[28:29], 1.0 op_sel_hi:[1,0]
	v_pk_add_f32 v[30:31], v[30:31], 1.0 op_sel_hi:[1,0]
	v_pk_add_f32 v[32:33], v[32:33], 1.0 op_sel_hi:[1,0]
	v_pk_add_f32 v[34:35], v[34:35], 1.0 op_sel_hi:[1,0]
	v_rcp_f32_e32 v30, v30
	v_rcp_f32_e32 v28, v28
	v_rcp_f32_e32 v29, v29
	v_rcp_f32_e32 v31, v31
	v_rcp_f32_e32 v34, v34
	v_rcp_f32_e32 v35, v35
	v_rcp_f32_e32 v32, v32
	v_rcp_f32_e32 v33, v33
	v_pk_mul_f32 v[18:19], v[22:23], v[18:19]
	v_pk_mul_f32 v[16:17], v[20:21], v[16:17]
	v_pk_mul_f32 v[20:21], v[28:29], v[18:19]
	v_pk_mul_f32 v[18:19], v[30:31], v[16:17]
	v_pk_mul_f32 v[26:27], v[32:33], v[26:27]
	v_pk_mul_f32 v[24:25], v[34:35], v[24:25]
	v_add_u32_e32 v22, 0xdc000, v140
	v_cvt_pk_bf16_f32 v16, v24, v25
	v_cvt_pk_bf16_f32 v17, v26, v27
	v_cvt_pk_bf16_f32 v18, v18, v19
	v_cvt_pk_bf16_f32 v19, v20, v21
	global_store_dwordx4 v22, v[16:19], s[14:15] nt
	v_pk_mul_f32 v[10:11], v[14:15], v[10:11]
	v_pk_mul_f32 v[8:9], v[12:13], v[8:9]
	v_pk_mul_f32 v[16:17], v[14:15], s[22:23] op_sel_hi:[1,0]
	v_pk_mul_f32 v[18:19], v[12:13], s[22:23] op_sel_hi:[1,0]
	v_pk_mul_f32 v[12:13], v[6:7], s[22:23] op_sel_hi:[1,0]
	v_pk_mul_f32 v[14:15], v[4:5], s[22:23] op_sel_hi:[1,0]
	v_exp_f32_e32 v12, v12
	v_exp_f32_e32 v14, v14
	v_exp_f32_e32 v13, v13
	v_exp_f32_e32 v15, v15
	v_exp_f32_e32 v18, v18
	v_exp_f32_e32 v16, v16
	v_exp_f32_e32 v17, v17
	v_exp_f32_e32 v19, v19
	v_pk_add_f32 v[12:13], v[12:13], 1.0 op_sel_hi:[1,0]
	v_pk_add_f32 v[14:15], v[14:15], 1.0 op_sel_hi:[1,0]
	v_pk_add_f32 v[16:17], v[16:17], 1.0 op_sel_hi:[1,0]
	v_pk_add_f32 v[18:19], v[18:19], 1.0 op_sel_hi:[1,0]
	v_rcp_f32_e32 v14, v14
	v_rcp_f32_e32 v12, v12
	v_rcp_f32_e32 v13, v13
	v_rcp_f32_e32 v15, v15
	v_rcp_f32_e32 v18, v18
	v_rcp_f32_e32 v19, v19
	v_rcp_f32_e32 v16, v16
	v_rcp_f32_e32 v17, v17
	v_pk_mul_f32 v[2:3], v[6:7], v[2:3]
	v_pk_mul_f32 v[0:1], v[4:5], v[0:1]
	v_pk_mul_f32 v[4:5], v[12:13], v[2:3]
	v_pk_mul_f32 v[2:3], v[14:15], v[0:1]
	v_add_u32_e32 v6, 0xf2000, v140
	s_andn2_b64 vcc, exec, s[6:7]
	s_mov_b64 s[6:7], -1
	v_pk_mul_f32 v[10:11], v[16:17], v[10:11]
	v_pk_mul_f32 v[8:9], v[18:19], v[8:9]
	v_cvt_pk_bf16_f32 v1, v10, v11
	v_cvt_pk_bf16_f32 v2, v2, v3
	v_cvt_pk_bf16_f32 v3, v4, v5
	s_nop 0
	v_cvt_pk_bf16_f32 v0, v8, v9
	global_store_dwordx4 v6, v[0:3], s[14:15] nt
	s_cbranch_vccnz .LBB0_1243
	s_andn2_b64 vcc, exec, s[0:1]
	s_cbranch_vccnz .LBB0_1242
	s_barrier
	s_branch .LBB0_1242

; __device__ __forceinline__ unsigned cvt_pk_bf16(float lo, float hi) { unsigned r; asm("v_cvt_pk_bf16_f32 %0, %1, %2" : "=v"(r) : "v"(lo), "v"(hi)); return r; }
;     __device__ __forceinline__ void operator()(const Acc& acc, const Unit& u, int wr, int wc, int fr, int fq) const {
;         const int row0 = u.pm * 256 + wr * 64 + fr, h0 = u.pn * 128 + wc * 32 + 8 * fq;
; #pragma unroll
;         for (int ai = 0; ai < 2; ++ai)
; #pragma unroll
;             for (int m = 0; m < 4; ++m) { bf16_t* rp = ACT + (size_t)(row0 + ai * 128 + m * 16) * FF + h0; float v[8];
; #pragma unroll
;                 for (int n = 0; n < 2; ++n) { const f32x4 a = acc[ai][0][m][n], b = acc[ai][1][m][n];
;                     const f32x4 t = a * (-LOG2E); f32x4 e; e.x = __builtin_amdgcn_exp2f(t.x); e.y = __builtin_amdgcn_exp2f(t.y); e.z = __builtin_amdgcn_exp2f(t.z); e.w = __builtin_amdgcn_exp2f(t.w);
;                     const f32x4 d = e + 1.0f; f32x4 r; r.x = __builtin_amdgcn_rcpf(d.x); r.y = __builtin_amdgcn_rcpf(d.y); r.z = __builtin_amdgcn_rcpf(d.z); r.w = __builtin_amdgcn_rcpf(d.w);
;                     const f32x4 o = (a * b) * r; v[4 * n + 0] = o.x; v[4 * n + 1] = o.y; v[4 * n + 2] = o.z; v[4 * n + 3] = o.w; }
;                 u32x4 w; w.x = cvt_pk_bf16(v[0], v[1]); w.y = cvt_pk_bf16(v[2], v[3]); w.z = cvt_pk_bf16(v[4], v[5]); w.w = cvt_pk_bf16(v[6], v[7]); __builtin_nontemporal_store(w, (u32x4*)rp); }
.LBB0_1866:
	v_pk_mul_f32 v[152:153], v[126:127], s[12:13] op_sel_hi:[1,0]
	v_pk_mul_f32 v[122:123], v[126:127], v[122:123]
	v_pk_mul_f32 v[126:127], v[116:117], s[12:13] op_sel_hi:[1,0]
	v_pk_mul_f32 v[154:155], v[124:125], s[12:13] op_sel_hi:[1,0]
	v_pk_mul_f32 v[120:121], v[124:125], v[120:121]
	v_pk_mul_f32 v[124:125], v[118:119], s[12:13] op_sel_hi:[1,0]
	v_exp_f32_e32 v126, v126
	v_exp_f32_e32 v127, v127
	v_exp_f32_e32 v154, v154
	v_exp_f32_e32 v152, v152
	v_exp_f32_e32 v153, v153
	v_exp_f32_e32 v155, v155
	v_exp_f32_e32 v124, v124
	v_exp_f32_e32 v125, v125
	v_pk_add_f32 v[126:127], v[126:127], 1.0 op_sel_hi:[1,0]
	v_pk_add_f32 v[152:153], v[152:153], 1.0 op_sel_hi:[1,0]
	v_pk_add_f32 v[154:155], v[154:155], 1.0 op_sel_hi:[1,0]
	v_pk_add_f32 v[124:125], v[124:125], 1.0 op_sel_hi:[1,0]
	v_rcp_f32_e32 v126, v126
	v_rcp_f32_e32 v127, v127
	v_rcp_f32_e32 v154, v154
	v_rcp_f32_e32 v155, v155
	v_rcp_f32_e32 v152, v152
	v_rcp_f32_e32 v153, v153
	v_rcp_f32_e32 v124, v124
	v_rcp_f32_e32 v125, v125
	v_lshl_or_b32 v150, s53, 7, v144
	v_lshl_add_u32 v148, s34, 8, v142
	v_pk_mul_f32 v[112:113], v[116:117], v[112:113]
	v_mul_u32_u24_e32 v140, s52, v148
	v_pk_mul_f32 v[114:115], v[118:119], v[114:115]
	v_pk_mul_f32 v[116:117], v[126:127], v[112:113]
	v_pk_mul_f32 v[122:123], v[152:153], v[122:123]
	v_pk_mul_f32 v[120:121], v[154:155], v[120:121]
	v_pk_mul_f32 v[118:119], v[124:125], v[114:115]
	v_lshl_add_u32 v140, v150, 1, v140
	v_cvt_pk_bf16_f32 v114, v120, v121
	v_cvt_pk_bf16_f32 v115, v122, v123
	v_cvt_pk_bf16_f32 v116, v116, v117
	v_cvt_pk_bf16_f32 v117, v118, v119
	global_store_dwordx4 v140, v[114:117], s[14:15] nt
	v_pk_mul_f32 v[106:107], v[110:111], v[106:107]
	v_pk_mul_f32 v[104:105], v[108:109], v[104:105]
	v_pk_mul_f32 v[114:115], v[110:111], s[12:13] op_sel_hi:[1,0]
	v_pk_mul_f32 v[116:117], v[108:109], s[12:13] op_sel_hi:[1,0]
	v_pk_mul_f32 v[108:109], v[102:103], s[12:13] op_sel_hi:[1,0]
	v_pk_mul_f32 v[110:111], v[100:101], s[12:13] op_sel_hi:[1,0]
	v_exp_f32_e32 v108, v108
	v_exp_f32_e32 v110, v110
	v_exp_f32_e32 v109, v109
	v_exp_f32_e32 v111, v111
	v_exp_f32_e32 v116, v116
	v_exp_f32_e32 v114, v114
	v_exp_f32_e32 v115, v115
	v_exp_f32_e32 v117, v117
	v_pk_add_f32 v[108:109], v[108:109], 1.0 op_sel_hi:[1,0]
	v_pk_add_f32 v[110:111], v[110:111], 1.0 op_sel_hi:[1,0]
	v_pk_add_f32 v[114:115], v[114:115], 1.0 op_sel_hi:[1,0]
	v_pk_add_f32 v[116:117], v[116:117], 1.0 op_sel_hi:[1,0]
	v_rcp_f32_e32 v110, v110
	v_rcp_f32_e32 v108, v108
	v_rcp_f32_e32 v109, v109
	v_rcp_f32_e32 v111, v111
	v_rcp_f32_e32 v116, v116
	v_rcp_f32_e32 v117, v117
	v_rcp_f32_e32 v114, v114
	v_rcp_f32_e32 v115, v115
	v_pk_mul_f32 v[98:99], v[102:103], v[98:99]
	v_pk_mul_f32 v[96:97], v[100:101], v[96:97]
	v_pk_mul_f32 v[100:101], v[108:109], v[98:99]
	v_pk_mul_f32 v[98:99], v[110:111], v[96:97]
	v_pk_mul_f32 v[106:107], v[114:115], v[106:107]
	v_pk_mul_f32 v[104:105], v[116:117], v[104:105]
	v_add_u32_e32 v102, 0x16000, v140
	v_cvt_pk_bf16_f32 v96, v104, v105
	v_cvt_pk_bf16_f32 v97, v106, v107
	v_cvt_pk_bf16_f32 v98, v98, v99
	v_cvt_pk_bf16_f32 v99, v100, v101
	global_store_dwordx4 v102, v[96:99], s[14:15] nt
	v_pk_mul_f32 v[90:91], v[94:95], v[90:91]
	v_pk_mul_f32 v[88:89], v[92:93], v[88:89]
	v_pk_mul_f32 v[96:97], v[94:95], s[12:13] op_sel_hi:[1,0]
	v_pk_mul_f32 v[98:99], v[92:93], s[12:13] op_sel_hi:[1,0]
	v_pk_mul_f32 v[92:93], v[86:87], s[12:13] op_sel_hi:[1,0]
	v_pk_mul_f32 v[94:95], v[84:85], s[12:13] op_sel_hi:[1,0]
	v_exp_f32_e32 v92, v92
	v_exp_f32_e32 v94, v94
	v_exp_f32_e32 v93, v93
	v_exp_f32_e32 v95, v95
	v_exp_f32_e32 v98, v98
	v_exp_f32_e32 v96, v96
	v_exp_f32_e32 v97, v97
	v_exp_f32_e32 v99, v99
	v_pk_add_f32 v[92:93], v[92:93], 1.0 op_sel_hi:[1,0]
	v_pk_add_f32 v[94:95], v[94:95], 1.0 op_sel_hi:[1,0]
	v_pk_add_f32 v[96:97], v[96:97], 1.0 op_sel_hi:[1,0]
	v_pk_add_f32 v[98:99], v[98:99], 1.0 op_sel_hi:[1,0]
	v_rcp_f32_e32 v94, v94
	v_rcp_f32_e32 v92, v92
	v_rcp_f32_e32 v93, v93
	v_rcp_f32_e32 v95, v95
	v_rcp_f32_e32 v98, v98
	v_rcp_f32_e32 v99, v99
	v_rcp_f32_e32 v96, v96
	v_rcp_f32_e32 v97, v97
	v_pk_mul_f32 v[82:83], v[86:87], v[82:83]
	v_pk_mul_f32 v[80:81], v[84:85], v[80:81]
	v_pk_mul_f32 v[84:85], v[92:93], v[82:83]
	v_pk_mul_f32 v[82:83], v[94:95], v[80:81]
	v_pk_mul_f32 v[90:91], v[96:97], v[90:91]
	v_pk_mul_f32 v[88:89], v[98:99], v[88:89]
	v_add_u32_e32 v86, 0x2c000, v140
	v_cvt_pk_bf16_f32 v80, v88, v89
	v_cvt_pk_bf16_f32 v81, v90, v91
	v_cvt_pk_bf16_f32 v82, v82, v83
	v_cvt_pk_bf16_f32 v83, v84, v85
	global_store_dwordx4 v86, v[80:83], s[14:15] nt
	v_pk_mul_f32 v[74:75], v[78:79], v[74:75]
	v_pk_mul_f32 v[72:73], v[76:77], v[72:73]
	v_pk_mul_f32 v[80:81], v[78:79], s[12:13] op_sel_hi:[1,0]
	v_pk_mul_f32 v[82:83], v[76:77], s[12:13] op_sel_hi:[1,0]
	v_pk_mul_f32 v[76:77], v[70:71], s[12:13] op_sel_hi:[1,0]
	v_pk_mul_f32 v[78:79], v[68:69], s[12:13] op_sel_hi:[1,0]
	v_exp_f32_e32 v76, v76
	v_exp_f32_e32 v78, v78
	v_exp_f32_e32 v77, v77
	v_exp_f32_e32 v79, v79
	v_exp_f32_e32 v82, v82
	v_exp_f32_e32 v80, v80
	v_exp_f32_e32 v81, v81
	v_exp_f32_e32 v83, v83
	v_pk_add_f32 v[76:77], v[76:77], 1.0 op_sel_hi:[1,0]
	v_pk_add_f32 v[78:79], v[78:79], 1.0 op_sel_hi:[1,0]
	v_pk_add_f32 v[80:81], v[80:81], 1.0 op_sel_hi:[1,0]
	v_pk_add_f32 v[82:83], v[82:83], 1.0 op_sel_hi:[1,0]
	v_rcp_f32_e32 v78, v78
	v_rcp_f32_e32 v76, v76
	v_rcp_f32_e32 v77, v77
	v_rcp_f32_e32 v79, v79
	v_rcp_f32_e32 v82, v82
	v_rcp_f32_e32 v83, v83
	v_rcp_f32_e32 v80, v80
	v_rcp_f32_e32 v81, v81
	v_pk_mul_f32 v[66:67], v[70:71], v[66:67]
	v_pk_mul_f32 v[64:65], v[68:69], v[64:65]
	v_pk_mul_f32 v[68:69], v[76:77], v[66:67]
	v_pk_mul_f32 v[66:67], v[78:79], v[64:65]
; __device__ __forceinline__ unsigned cvt_pk_bf16(float lo, float hi) { unsigned r; asm("v_cvt_pk_bf16_f32 %0, %1, %2" : "=v"(r) : "v"(lo), "v"(hi)); return r; }
;     __device__ __forceinline__ void operator()(const Acc& acc, const Unit& u, int wr, int wc, int fr, int fq) const {
;         const int row0 = u.pm * 256 + wr * 64 + fr, h0 = u.pn * 128 + wc * 32 + 8 * fq;
; #pragma unroll
;         for (int ai = 0; ai < 2; ++ai)
; #pragma unroll
;             for (int m = 0; m < 4; ++m) { bf16_t* rp = ACT + (size_t)(row0 + ai * 128 + m * 16) * FF + h0; float v[8];
; #pragma unroll
;                 for (int n = 0; n < 2; ++n) { const f32x4 a = acc[ai][0][m][n], b = acc[ai][1][m][n];
;                     const f32x4 t = a * (-LOG2E); f32x4 e; e.x = __builtin_amdgcn_exp2f(t.x); e.y = __builtin_amdgcn_exp2f(t.y); e.z = __builtin_amdgcn_exp2f(t.z); e.w = __builtin_amdgcn_exp2f(t.w);
;                     const f32x4 d = e + 1.0f; f32x4 r; r.x = __builtin_amdgcn_rcpf(d.x); r.y = __builtin_amdgcn_rcpf(d.y); r.z = __builtin_amdgcn_rcpf(d.z); r.w = __builtin_amdgcn_rcpf(d.w);
;                     const f32x4 o = (a * b) * r; v[4 * n + 0] = o.x; v[4 * n + 1] = o.y; v[4 * n + 2] = o.z; v[4 * n + 3] = o.w; }
;                 u32x4 w; w.x = cvt_pk_bf16(v[0], v[1]); w.y = cvt_pk_bf16(v[2], v[3]); w.z = cvt_pk_bf16(v[4], v[5]); w.w = cvt_pk_bf16(v[6], v[7]); __builtin_nontemporal_store(w, (u32x4*)rp); }
	v_pk_mul_f32 v[74:75], v[80:81], v[74:75]
	v_pk_mul_f32 v[72:73], v[82:83], v[72:73]
	v_add_u32_e32 v70, 0x42000, v140
	v_cvt_pk_bf16_f32 v64, v72, v73
	v_cvt_pk_bf16_f32 v65, v74, v75
	v_cvt_pk_bf16_f32 v66, v66, v67
	v_cvt_pk_bf16_f32 v67, v68, v69
	global_store_dwordx4 v70, v[64:67], s[14:15] nt
	v_pk_mul_f32 v[58:59], v[62:63], v[58:59]
	v_pk_mul_f32 v[56:57], v[60:61], v[56:57]
	v_pk_mul_f32 v[64:65], v[62:63], s[12:13] op_sel_hi:[1,0]
	v_pk_mul_f32 v[66:67], v[60:61], s[12:13] op_sel_hi:[1,0]
	v_pk_mul_f32 v[60:61], v[54:55], s[12:13] op_sel_hi:[1,0]
	v_pk_mul_f32 v[62:63], v[52:53], s[12:13] op_sel_hi:[1,0]
	v_exp_f32_e32 v60, v60
	v_exp_f32_e32 v62, v62
	v_exp_f32_e32 v61, v61
	v_exp_f32_e32 v63, v63
	v_exp_f32_e32 v66, v66
	v_exp_f32_e32 v64, v64
	v_exp_f32_e32 v65, v65
	v_exp_f32_e32 v67, v67
	v_pk_add_f32 v[60:61], v[60:61], 1.0 op_sel_hi:[1,0]
	v_pk_add_f32 v[62:63], v[62:63], 1.0 op_sel_hi:[1,0]
	v_pk_add_f32 v[64:65], v[64:65], 1.0 op_sel_hi:[1,0]
	v_pk_add_f32 v[66:67], v[66:67], 1.0 op_sel_hi:[1,0]
	v_rcp_f32_e32 v62, v62
	v_rcp_f32_e32 v60, v60
	v_rcp_f32_e32 v61, v61
	v_rcp_f32_e32 v63, v63
	v_rcp_f32_e32 v66, v66
	v_rcp_f32_e32 v67, v67
	v_rcp_f32_e32 v64, v64
	v_rcp_f32_e32 v65, v65
	v_pk_mul_f32 v[50:51], v[54:55], v[50:51]
	v_pk_mul_f32 v[48:49], v[52:53], v[48:49]
	v_pk_mul_f32 v[52:53], v[60:61], v[50:51]
	v_pk_mul_f32 v[50:51], v[62:63], v[48:49]
	v_pk_mul_f32 v[58:59], v[64:65], v[58:59]
	v_pk_mul_f32 v[56:57], v[66:67], v[56:57]
	v_add_u32_e32 v54, 0xb0000, v140
	v_cvt_pk_bf16_f32 v48, v56, v57
	v_cvt_pk_bf16_f32 v49, v58, v59
	v_cvt_pk_bf16_f32 v50, v50, v51
	v_cvt_pk_bf16_f32 v51, v52, v53
	global_store_dwordx4 v54, v[48:51], s[14:15] nt
	v_pk_mul_f32 v[42:43], v[46:47], v[42:43]
	v_pk_mul_f32 v[40:41], v[44:45], v[40:41]
	v_pk_mul_f32 v[48:49], v[46:47], s[12:13] op_sel_hi:[1,0]
	v_pk_mul_f32 v[50:51], v[44:45], s[12:13] op_sel_hi:[1,0]
	v_pk_mul_f32 v[44:45], v[38:39], s[12:13] op_sel_hi:[1,0]
	v_pk_mul_f32 v[46:47], v[36:37], s[12:13] op_sel_hi:[1,0]
	v_exp_f32_e32 v44, v44
	v_exp_f32_e32 v46, v46
	v_exp_f32_e32 v45, v45
	v_exp_f32_e32 v47, v47
	v_exp_f32_e32 v50, v50
	v_exp_f32_e32 v48, v48
	v_exp_f32_e32 v49, v49
	v_exp_f32_e32 v51, v51
	v_pk_add_f32 v[44:45], v[44:45], 1.0 op_sel_hi:[1,0]
	v_pk_add_f32 v[46:47], v[46:47], 1.0 op_sel_hi:[1,0]
	v_pk_add_f32 v[48:49], v[48:49], 1.0 op_sel_hi:[1,0]
	v_pk_add_f32 v[50:51], v[50:51], 1.0 op_sel_hi:[1,0]
	v_rcp_f32_e32 v46, v46
	v_rcp_f32_e32 v44, v44
	v_rcp_f32_e32 v45, v45
	v_rcp_f32_e32 v47, v47
	v_rcp_f32_e32 v50, v50
	v_rcp_f32_e32 v51, v51
	v_rcp_f32_e32 v48, v48
	v_rcp_f32_e32 v49, v49
	v_pk_mul_f32 v[34:35], v[38:39], v[34:35]
	v_pk_mul_f32 v[32:33], v[36:37], v[32:33]
	v_pk_mul_f32 v[36:37], v[44:45], v[34:35]
	v_pk_mul_f32 v[34:35], v[46:47], v[32:33]
	v_pk_mul_f32 v[42:43], v[48:49], v[42:43]
	v_pk_mul_f32 v[40:41], v[50:51], v[40:41]
	v_add_u32_e32 v38, 0xc6000, v140
	v_cvt_pk_bf16_f32 v32, v40, v41
	v_cvt_pk_bf16_f32 v33, v42, v43
	v_cvt_pk_bf16_f32 v34, v34, v35
	v_cvt_pk_bf16_f32 v35, v36, v37
	global_store_dwordx4 v38, v[32:35], s[14:15] nt
	v_pk_mul_f32 v[26:27], v[30:31], v[26:27]
	v_pk_mul_f32 v[24:25], v[28:29], v[24:25]
	v_pk_mul_f32 v[32:33], v[30:31], s[12:13] op_sel_hi:[1,0]
	v_pk_mul_f32 v[34:35], v[28:29], s[12:13] op_sel_hi:[1,0]
	v_pk_mul_f32 v[28:29], v[22:23], s[12:13] op_sel_hi:[1,0]
	v_pk_mul_f32 v[30:31], v[20:21], s[12:13] op_sel_hi:[1,0]
	v_exp_f32_e32 v28, v28
	v_exp_f32_e32 v30, v30
	v_exp_f32_e32 v29, v29
	v_exp_f32_e32 v31, v31
	v_exp_f32_e32 v34, v34
	v_exp_f32_e32 v32, v32
	v_exp_f32_e32 v33, v33
	v_exp_f32_e32 v35, v35
	v_pk_add_f32 v[28:29], v[28:29], 1.0 op_sel_hi:[1,0]
	v_pk_add_f32 v[30:31], v[30:31], 1.0 op_sel_hi:[1,0]
	v_pk_add_f32 v[32:33], v[32:33], 1.0 op_sel_hi:[1,0]
	v_pk_add_f32 v[34:35], v[34:35], 1.0 op_sel_hi:[1,0]
	v_rcp_f32_e32 v30, v30
	v_rcp_f32_e32 v28, v28
	v_rcp_f32_e32 v29, v29
	v_rcp_f32_e32 v31, v31
	v_rcp_f32_e32 v34, v34
	v_rcp_f32_e32 v35, v35
	v_rcp_f32_e32 v32, v32
	v_rcp_f32_e32 v33, v33
	v_pk_mul_f32 v[18:19], v[22:23], v[18:19]
	v_pk_mul_f32 v[16:17], v[20:21], v[16:17]
	v_pk_mul_f32 v[20:21], v[28:29], v[18:19]
	v_pk_mul_f32 v[18:19], v[30:31], v[16:17]
	v_pk_mul_f32 v[26:27], v[32:33], v[26:27]
	v_pk_mul_f32 v[24:25], v[34:35], v[24:25]
	v_add_u32_e32 v22, 0xdc000, v140
	v_cvt_pk_bf16_f32 v16, v24, v25
	v_cvt_pk_bf16_f32 v17, v26, v27
	v_cvt_pk_bf16_f32 v18, v18, v19
	v_cvt_pk_bf16_f32 v19, v20, v21
	global_store_dwordx4 v22, v[16:19], s[14:15] nt
	v_pk_mul_f32 v[10:11], v[14:15], v[10:11]
	v_pk_mul_f32 v[8:9], v[12:13], v[8:9]
	v_pk_mul_f32 v[16:17], v[14:15], s[12:13] op_sel_hi:[1,0]
	v_pk_mul_f32 v[18:19], v[12:13], s[12:13] op_sel_hi:[1,0]
	v_pk_mul_f32 v[12:13], v[6:7], s[12:13] op_sel_hi:[1,0]
	v_pk_mul_f32 v[14:15], v[4:5], s[12:13] op_sel_hi:[1,0]
	v_exp_f32_e32 v12, v12
	v_exp_f32_e32 v14, v14
	v_exp_f32_e32 v13, v13
	v_exp_f32_e32 v15, v15
	v_exp_f32_e32 v18, v18
	v_exp_f32_e32 v16, v16
	v_exp_f32_e32 v17, v17
	v_exp_f32_e32 v19, v19
	v_pk_add_f32 v[12:13], v[12:13], 1.0 op_sel_hi:[1,0]
	v_pk_add_f32 v[14:15], v[14:15], 1.0 op_sel_hi:[1,0]
	v_pk_add_f32 v[16:17], v[16:17], 1.0 op_sel_hi:[1,0]
	v_pk_add_f32 v[18:19], v[18:19], 1.0 op_sel_hi:[1,0]
	v_rcp_f32_e32 v14, v14
	v_rcp_f32_e32 v12, v12
	v_rcp_f32_e32 v13, v13
	v_rcp_f32_e32 v15, v15
	v_rcp_f32_e32 v18, v18
	v_rcp_f32_e32 v19, v19
	v_rcp_f32_e32 v16, v16
	v_rcp_f32_e32 v17, v17
	v_pk_mul_f32 v[2:3], v[6:7], v[2:3]
	v_pk_mul_f32 v[0:1], v[4:5], v[0:1]
	v_pk_mul_f32 v[4:5], v[12:13], v[2:3]
	v_pk_mul_f32 v[2:3], v[14:15], v[0:1]
	v_add_u32_e32 v6, 0xf2000, v140
	s_andn2_b64 vcc, exec, s[6:7]
	s_mov_b64 s[6:7], -1
	v_pk_mul_f32 v[10:11], v[16:17], v[10:11]
	v_pk_mul_f32 v[8:9], v[18:19], v[8:9]
	v_cvt_pk_bf16_f32 v1, v10, v11
	v_cvt_pk_bf16_f32 v2, v2, v3
	v_cvt_pk_bf16_f32 v3, v4, v5
	s_nop 0
	v_cvt_pk_bf16_f32 v0, v8, v9
	global_store_dwordx4 v6, v[0:3], s[14:15] nt
	s_cbranch_vccnz .LBB0_1859
	s_andn2_b64 vcc, exec, s[0:1]
	s_cbranch_vccnz .LBB0_1858
	s_barrier
	s_branch .LBB0_1858
